# LN2: per-column vectors staged in LDS like LN1 (gain/bias always, next-layer scale/shift when present); row loop waits cover LDS only
# speedup vs baseline: 1.0171x; 1.0050x over previous
; __device__ __forceinline__ int otid() { int t = threadIdx.x; asm volatile("" : "+v"(t)); return t; }
; __device__ __forceinline__ void phase_ln(const float* z, float* xo, const float* __restrict__ g, const float* __restrict__ b, const float* __restrict__ sc, const float* __restrict__ sh, bf16_t* __restrict__ u) {
;     const int tid_o = otid(), lane = tid_o & 63, wave = tid_o >> 6;
;     const int stride = gridDim.x * 8;
;     for (int r = blockIdx.x * 8 + wave; r < S; r += 2 * stride) {
;         const bool hasB = r + stride < S; const int rr[2] = {r, hasB ? r + stride : r};
;     ...
;         for (int j = 0; j < 8; ++j) { const int col = j * 256 + 4 * lane;
;             const f32x4 gg = *(const f32x4*)(g + col), bb = *(const f32x4*)(b + col);
;             f32x4 s1 = {0.f, 0.f, 0.f, 0.f}, h1 = {0.f, 0.f, 0.f, 0.f};
;             if (u) { s1 = *(const f32x4*)(sc + col) + 1.0f; h1 = *(const f32x4*)(sh + col); }
.LBB0_1328:
	v_mov_b32_e32 v10, v216
	v_readlane_b32 s2, v254, 9
	v_ashrrev_i32_e32 v0, 6, v10
	s_nop 0
	v_add_u32_e32 v76, s2, v0
	v_cmp_gt_i32_e32 vcc, s22, v76
	s_and_saveexec_b64 s[2:3], vcc
	s_cbranch_execz .LBB0_1394
	v_readlane_b32 s16, v254, 46
	v_readlane_b32 s17, v254, 47
	s_lshl_b32 s90, s16, 11
	s_lshl_b64 s[16:17], s[90:91], 2
	s_add_u32 s14, s14, s16
	s_addc_u32 s15, s15, s17
	v_lshlrev_b32_e32 v0, 2, v10
	s_add_u32 s16, s10, s16
	v_and_b32_e32 v11, 0xfc, v0
	s_addc_u32 s17, s11, s17
	v_lshlrev_b32_e32 v0, 2, v11
	v_mov_b32_e32 v252, v0
	v_lshl_add_u64 v[78:79], s[14:15], 0, v[0:1]
	v_lshl_add_u64 v[80:81], s[16:17], 0, v[0:1]
	flat_load_dwordx4 v[2:5], v[78:79]
	flat_load_dwordx4 v[6:9], v[80:81]
	s_add_u32 s18, s8, 0x2000
	s_addc_u32 s19, s9, 0
	v_lshlrev_b32_e32 v253, 4, v10
	global_load_dwordx4 v[240:243], v253, s[14:15]
	global_load_dwordx4 v[244:247], v253, s[16:17]
	s_cmp_eq_u64 s[12:13], 0
	s_cbranch_scc1 .Lln2_nofill
	global_load_dwordx4 v[248:251], v253, s[18:19]
	global_load_dwordx4 v[236:239], v253, s[6:7]
.Lln2_nofill:
	s_waitcnt vmcnt(0)
	ds_write_b128 v253, v[240:243]
	ds_write_b128 v253, v[244:247] offset:8192
	ds_write_b128 v253, v[248:251] offset:16384
	ds_write_b128 v253, v[236:239] offset:24576
	s_waitcnt lgkmcnt(0)
	s_barrier
	v_lshl_add_u64 v[12:13], s[0:1], 0, v[0:1]
	s_mov_b64 s[8:9], 0xb828000
	v_lshl_add_u64 v[82:83], v[12:13], 0, s[8:9]
	v_lshlrev_b32_e32 v12, 1, v11
	v_mov_b32_e32 v13, v1
	v_lshl_add_u64 v[90:91], s[12:13], 0, v[12:13]
	v_or_b32_e32 v12, 0x400, v0
	v_lshl_add_u64 v[92:93], s[18:19], 0, v[12:13]
	v_or_b32_e32 v12, 0x800, v0
	v_lshl_add_u64 v[94:95], s[18:19], 0, v[12:13]
	v_or_b32_e32 v12, 0xc00, v0
	v_lshl_add_u64 v[96:97], s[18:19], 0, v[12:13]
	v_or_b32_e32 v12, 0x1000, v0
	v_lshl_add_u64 v[98:99], s[14:15], 0, v[12:13]
	v_lshl_add_u64 v[100:101], s[16:17], 0, v[12:13]
	v_lshl_add_u64 v[102:103], s[6:7], 0, v[12:13]
	v_lshl_add_u64 v[104:105], s[18:19], 0, v[12:13]
	v_lshl_add_u64 v[106:107], s[4:5], 0, v[12:13]
	v_or_b32_e32 v12, 0x1400, v0
	v_lshl_add_u64 v[108:109], s[14:15], 0, v[12:13]
	v_lshl_add_u64 v[110:111], s[16:17], 0, v[12:13]
	v_lshl_add_u64 v[112:113], s[6:7], 0, v[12:13]
	v_lshl_add_u64 v[114:115], s[18:19], 0, v[12:13]
	v_lshl_add_u64 v[116:117], s[4:5], 0, v[12:13]
	v_or_b32_e32 v12, 0x1800, v0
	v_ashrrev_i32_e32 v77, 31, v76
	v_lshl_add_u64 v[118:119], s[14:15], 0, v[12:13]
	v_lshl_add_u64 v[120:121], s[16:17], 0, v[12:13]
	v_lshl_add_u64 v[122:123], s[6:7], 0, v[12:13]
	v_lshl_add_u64 v[124:125], s[18:19], 0, v[12:13]
	v_lshl_add_u64 v[126:127], s[4:5], 0, v[12:13]
	v_and_b32_e32 v14, 63, v10
	v_lshlrev_b64 v[12:13], 12, v[76:77]
	s_cmp_lg_u64 s[12:13], 0
	v_lshl_add_u64 v[84:85], s[6:7], 0, v[0:1]
	v_lshl_add_u64 v[86:87], s[18:19], 0, v[0:1]
	v_lshl_add_u64 v[88:89], s[4:5], 0, v[0:1]
	v_or_b32_e32 v0, 0x1c00, v0
	v_lshlrev_b64 v[10:11], 13, v[76:77]
	v_lshl_or_b32 v12, v14, 3, v12
	s_mov_b64 s[8:9], 0
	s_cselect_b64 s[10:11], -1, 0
	v_lshl_add_u64 v[128:129], s[14:15], 0, v[0:1]
	v_lshl_add_u64 v[130:131], s[16:17], 0, v[0:1]
	v_lshl_add_u64 v[132:133], s[6:7], 0, v[0:1]
	v_lshl_add_u64 v[134:135], s[18:19], 0, v[0:1]
	v_lshl_add_u64 v[136:137], s[4:5], 0, v[0:1]
	v_lshlrev_b32_e32 v0, 4, v14
	v_lshl_add_u64 v[138:139], s[0:1], 0, v[10:11]
	v_lshl_add_u64 v[140:141], s[12:13], 0, v[12:13]
	v_lshl_add_u64 v[142:143], s[4:5], 0, v[10:11]
	s_branch .LBB0_1331

; __device__ __forceinline__ void phase_ln(const float* z, float* xo, const float* __restrict__ g, const float* __restrict__ b, const float* __restrict__ sc, const float* __restrict__ sh, bf16_t* __restrict__ u) {
;     ...
;     for (int r = blockIdx.x * 8 + wave; r < S; r += 2 * stride) {
;         const bool hasB = r + stride < S; const int rr[2] = {r, hasB ? r + stride : r};
;         f32x4 v[2][8]; float s[2] = {0.f, 0.f};
; #pragma unroll
;         for (int k = 0; k < 2; ++k) { const float* zr = z + (size_t)rr[k] * DM;
; #pragma unroll
;             for (int j = 0; j < 8; ++j) v[k][j] = *(const f32x4*)(zr + j * 256 + 4 * lane); }
; #pragma unroll
;         for (int k = 0; k < 2; ++k)
; #pragma unroll
;             for (int j = 0; j < 8; ++j) s[k] += (v[k][j][0] + v[k][j][1]) + (v[k][j][2] + v[k][j][3]);
;         float mean[2], rstd[2];
; #pragma unroll
;         for (int k = 0; k < 2; ++k) { mean[k] = wave_sum(s[k]) * (1.0f / DM); float q = 0.f;
.LBB0_1331:
	v_add_u32_e32 v10, s20, v76
	v_cmp_gt_i32_e64 s[4:5], s22, v10
	v_mov_b32_e32 v164, 0
	v_mov_b32_e32 v165, 0
	v_cndmask_b32_e64 v144, v76, v10, s[4:5]
	v_lshl_add_u64 v[10:11], v[138:139], 0, v[0:1]
	v_add_co_u32_e32 v12, vcc, 0xb828000, v10
	v_ashrrev_i32_e32 v145, 31, v144
	s_nop 0
	v_addc_co_u32_e32 v13, vcc, 0, v11, vcc
	flat_load_dwordx4 v[70:73], v[12:13]
	flat_load_dwordx4 v[62:65], v[12:13] offset:1024
	flat_load_dwordx4 v[54:57], v[12:13] offset:2048
	flat_load_dwordx4 v[46:49], v[12:13] offset:3072
	v_add_co_u32_e32 v10, vcc, 0xb829000, v10
	v_lshlrev_b64 v[146:147], 13, v[144:145]
	s_nop 0
	v_addc_co_u32_e32 v11, vcc, 0, v11, vcc
	flat_load_dwordx4 v[38:41], v[10:11]
	flat_load_dwordx4 v[30:33], v[10:11] offset:1024
	flat_load_dwordx4 v[22:25], v[10:11] offset:2048
	flat_load_dwordx4 v[14:17], v[10:11] offset:3072
	v_lshl_add_u64 v[10:11], v[82:83], 0, v[146:147]
	flat_load_dwordx4 v[66:69], v[10:11]
	flat_load_dwordx4 v[58:61], v[10:11] offset:1024
	flat_load_dwordx4 v[50:53], v[10:11] offset:2048
	flat_load_dwordx4 v[42:45], v[10:11] offset:3072
	v_add_co_u32_e32 v10, vcc, s24, v10
	s_waitcnt vmcnt(0) lgkmcnt(0)
	v_add_f32_e32 v74, v70, v71
	v_addc_co_u32_e32 v11, vcc, 0, v11, vcc
	flat_load_dwordx4 v[34:37], v[10:11]
	flat_load_dwordx4 v[26:29], v[10:11] offset:1024
	flat_load_dwordx4 v[18:21], v[10:11] offset:2048
	s_nop 0
	flat_load_dwordx4 v[10:13], v[10:11] offset:3072
	v_add_f32_e32 v75, v72, v73
	v_add_f32_e32 v74, v74, v75
	v_add_f32_e32 v75, v62, v63
	v_add_f32_e32 v77, v64, v65
	v_add_f32_e32 v74, 0, v74
	v_add_f32_e32 v75, v75, v77
	v_add_f32_e32 v74, v74, v75
	v_add_f32_e32 v75, v54, v55
	v_add_f32_e32 v77, v56, v57
	v_add_f32_e32 v75, v75, v77
	v_add_f32_e32 v74, v74, v75
	v_add_f32_e32 v75, v46, v47
	v_add_f32_e32 v77, v48, v49
	v_add_f32_e32 v75, v75, v77
	v_add_f32_e32 v74, v74, v75
	v_add_f32_e32 v75, v38, v39
	v_add_f32_e32 v77, v40, v41
	v_add_f32_e32 v75, v75, v77
	v_add_f32_e32 v74, v74, v75
	v_add_f32_e32 v75, v30, v31
	v_add_f32_e32 v77, v32, v33
	v_add_f32_e32 v75, v75, v77
	v_add_f32_e32 v74, v74, v75
	v_add_f32_e32 v75, v22, v23
	v_add_f32_e32 v77, v24, v25
	v_add_f32_e32 v75, v75, v77
	v_add_f32_e32 v74, v74, v75
	v_add_f32_e32 v75, v14, v15
	v_add_f32_e32 v77, v16, v17
	v_add_f32_e32 v75, v75, v77
	v_add_f32_e32 v74, v74, v75
	v_add_f32_e32 v75, v66, v67
	v_add_f32_e32 v77, v68, v69
	v_add_f32_e32 v75, v75, v77
	v_add_f32_e32 v77, v58, v59
	v_add_f32_e32 v148, v60, v61
	v_add_f32_e32 v75, 0, v75
	v_add_f32_e32 v77, v77, v148
	v_add_f32_e32 v75, v75, v77
	v_add_f32_e32 v77, v50, v51
	v_add_f32_e32 v148, v52, v53
	v_add_f32_e32 v77, v77, v148
	v_add_f32_e32 v75, v75, v77
	v_add_f32_e32 v77, v42, v43
	v_add_f32_e32 v148, v44, v45
	v_add_f32_e32 v77, v77, v148
	v_add_f32_e32 v75, v75, v77
	v_add_f32_dpp v74, v74, v74 quad_perm:[1,0,3,2] row_mask:0xf bank_mask:0xf bound_ctrl:1
	s_andn2_b64 vcc, exec, s[10:11]
	s_waitcnt vmcnt(0) lgkmcnt(0)
	v_add_f32_e32 v77, v34, v35
	v_add_f32_e32 v148, v36, v37
	v_add_f32_e32 v77, v77, v148
	v_add_f32_e32 v75, v75, v77
	v_add_f32_e32 v77, v26, v27
	v_add_f32_e32 v148, v28, v29
	v_add_f32_e32 v77, v77, v148
	v_add_f32_e32 v75, v75, v77
	v_add_f32_e32 v77, v18, v19
	v_add_f32_e32 v148, v20, v21
	v_add_f32_e32 v77, v77, v148
	v_add_f32_dpp v74, v74, v74 quad_perm:[2,3,0,1] row_mask:0xf bank_mask:0xf bound_ctrl:1
	v_add_f32_e32 v75, v75, v77
	v_add_f32_e32 v77, v10, v11
	v_add_f32_e32 v148, v12, v13
	v_add_f32_dpp v74, v74, v74 row_half_mirror row_mask:0xf bank_mask:0xf bound_ctrl:1
	v_add_f32_e32 v77, v77, v148
	v_add_f32_e32 v75, v75, v77
	v_add_f32_dpp v74, v74, v74 row_mirror row_mask:0xf bank_mask:0xf bound_ctrl:1
	v_mov_b32_e32 v77, v74
	s_nop 1
	v_permlane16_swap_b32_e32 v74, v77
	v_add_f32_e32 v74, v74, v77
	v_mov_b32_e32 v77, v74
	s_nop 1
	v_permlane32_swap_b32_e32 v74, v77
	v_add_f32_e32 v74, v74, v77
	v_fmamk_f32 v155, v74, 0xba000000, v73
	v_fmamk_f32 v71, v74, 0xba000000, v71
	v_fmamk_f32 v169, v74, 0xba000000, v65
	v_fmamk_f32 v63, v74, 0xba000000, v63
	v_fmamk_f32 v154, v74, 0xba000000, v72
	v_fmac_f32_e32 v70, 0xba000000, v74
	v_mul_f32_e32 v72, v71, v71
	v_mul_f32_e32 v73, v155, v155
	v_fmamk_f32 v168, v74, 0xba000000, v64
	v_fmac_f32_e32 v62, 0xba000000, v74
	v_mul_f32_e32 v64, v63, v63
	v_mul_f32_e32 v65, v169, v169
	v_fmamk_f32 v167, v74, 0xba000000, v57
	v_fmamk_f32 v55, v74, 0xba000000, v55
	v_fmac_f32_e32 v72, v70, v70
	v_fmac_f32_e32 v73, v154, v154
	v_fmac_f32_e32 v64, v62, v62
	v_fmac_f32_e32 v65, v168, v168
	v_fmamk_f32 v166, v74, 0xba000000, v56
	v_fmac_f32_e32 v54, 0xba000000, v74
	v_mul_f32_e32 v56, v55, v55
	v_mul_f32_e32 v57, v167, v167
	v_fmamk_f32 v163, v74, 0xba000000, v49
	v_fmamk_f32 v47, v74, 0xba000000, v47
	v_add_f32_e32 v72, v72, v73
	v_add_f32_e32 v64, v64, v65
	v_fmac_f32_e32 v56, v54, v54
	v_fmac_f32_e32 v57, v166, v166
	v_fmamk_f32 v162, v74, 0xba000000, v48
	v_fmac_f32_e32 v46, 0xba000000, v74
	v_mul_f32_e32 v48, v47, v47
	v_mul_f32_e32 v49, v163, v163
	v_fmamk_f32 v161, v74, 0xba000000, v41
	v_fmamk_f32 v39, v74, 0xba000000, v39
	v_add_f32_e32 v64, v72, v64
	v_add_f32_e32 v56, v56, v57
	v_fmac_f32_e32 v48, v46, v46
	v_fmac_f32_e32 v49, v162, v162
	v_fmamk_f32 v160, v74, 0xba000000, v40
	v_fmac_f32_e32 v38, 0xba000000, v74
	v_mul_f32_e32 v40, v39, v39
	v_mul_f32_e32 v41, v161, v161
	v_fmamk_f32 v159, v74, 0xba000000, v33
	v_fmamk_f32 v31, v74, 0xba000000, v31
	v_add_f32_e32 v56, v56, v64
	v_add_f32_e32 v48, v48, v49
	v_fmac_f32_e32 v40, v38, v38
	v_fmac_f32_e32 v41, v160, v160
	v_fmamk_f32 v158, v74, 0xba000000, v32
	v_fmac_f32_e32 v30, 0xba000000, v74
	v_mul_f32_e32 v32, v31, v31
	v_mul_f32_e32 v33, v159, v159
; __device__ __forceinline__ void phase_ln(const float* z, float* xo, const float* __restrict__ g, const float* __restrict__ b, const float* __restrict__ sc, const float* __restrict__ sh, bf16_t* __restrict__ u) {
;     ...
;         for (int k = 0; k < 2; ++k) { mean[k] = wave_sum(s[k]) * (1.0f / DM); float q = 0.f;
; #pragma unroll
;             for (int j = 0; j < 8; ++j) { const f32x4 d = v[k][j] - mean[k]; q += (d[0] * d[0] + d[1] * d[1]) + (d[2] * d[2] + d[3] * d[3]); }
;             rstd[k] = 1.0f / sqrtf(wave_sum(q) * (1.0f / DM) + 1e-5f); }
; #pragma unroll
;         for (int j = 0; j < 8; ++j) { const int col = j * 256 + 4 * lane;
;             const f32x4 gg = *(const f32x4*)(g + col), bb = *(const f32x4*)(b + col);
;             f32x4 s1 = {0.f, 0.f, 0.f, 0.f}, h1 = {0.f, 0.f, 0.f, 0.f};
;             if (u) { s1 = *(const f32x4*)(sc + col) + 1.0f; h1 = *(const f32x4*)(sh + col); }
	v_fmamk_f32 v153, v74, 0xba000000, v25
	v_fmamk_f32 v23, v74, 0xba000000, v23
	v_add_f32_e32 v48, v48, v56
	v_add_f32_e32 v40, v40, v41
	v_fmac_f32_e32 v32, v30, v30
	v_fmac_f32_e32 v33, v158, v158
	v_fmamk_f32 v152, v74, 0xba000000, v24
	v_fmac_f32_e32 v22, 0xba000000, v74
	v_mul_f32_e32 v24, v23, v23
	v_mul_f32_e32 v25, v153, v153
	v_fmamk_f32 v149, v74, 0xba000000, v17
	v_fmamk_f32 v15, v74, 0xba000000, v15
	v_add_f32_e32 v40, v40, v48
	v_add_f32_e32 v32, v32, v33
	v_fmac_f32_e32 v24, v22, v22
	v_fmac_f32_e32 v25, v152, v152
	v_fmamk_f32 v148, v74, 0xba000000, v16
	v_fmac_f32_e32 v14, 0xba000000, v74
	v_mul_f32_e32 v16, v15, v15
	v_mul_f32_e32 v17, v149, v149
	v_add_f32_e32 v32, v32, v40
	v_add_f32_e32 v24, v24, v25
	v_fmac_f32_e32 v16, v14, v14
	v_fmac_f32_e32 v17, v148, v148
	v_add_f32_e32 v24, v24, v32
	v_add_f32_e32 v16, v16, v17
	v_add_f32_e32 v16, v16, v24
	v_mov_b32_e32 v73, 0
	v_mov_b32_e32 v74, 0
	v_add_f32_dpp v16, v16, v16 quad_perm:[1,0,3,2] row_mask:0xf bank_mask:0xf bound_ctrl:1
	s_nop 1
	v_add_f32_dpp v16, v16, v16 quad_perm:[2,3,0,1] row_mask:0xf bank_mask:0xf bound_ctrl:1
	s_nop 1
	v_add_f32_dpp v16, v16, v16 row_half_mirror row_mask:0xf bank_mask:0xf bound_ctrl:1
	s_nop 1
	v_add_f32_dpp v16, v16, v16 row_mirror row_mask:0xf bank_mask:0xf bound_ctrl:1
	v_mov_b32_e32 v17, v16
	s_nop 1
	v_permlane16_swap_b32_e32 v16, v17
	v_add_f32_e32 v77, v16, v17
	s_nop 0
	v_add_f32_dpp v16, v75, v75 quad_perm:[1,0,3,2] row_mask:0xf bank_mask:0xf bound_ctrl:1
	v_mov_b32_e32 v156, v77
	s_nop 1
	v_permlane32_swap_b32_e32 v77, v156
	v_add_f32_dpp v16, v16, v16 quad_perm:[2,3,0,1] row_mask:0xf bank_mask:0xf bound_ctrl:1
	v_mov_b32_e32 v75, 0
	s_nop 0
	v_add_f32_dpp v16, v16, v16 row_half_mirror row_mask:0xf bank_mask:0xf bound_ctrl:1
	s_nop 1
	v_add_f32_dpp v16, v16, v16 row_mirror row_mask:0xf bank_mask:0xf bound_ctrl:1
	v_mov_b32_e32 v17, v16
	s_nop 1
	v_permlane16_swap_b32_e32 v16, v17
	v_add_f32_e32 v16, v16, v17
	v_mov_b32_e32 v17, v16
	s_nop 1
	v_permlane32_swap_b32_e32 v16, v17
	v_add_f32_e32 v72, v16, v17
	v_fmamk_f32 v65, v72, 0xba000000, v69
	v_fmamk_f32 v67, v72, 0xba000000, v67
	v_fmamk_f32 v64, v72, 0xba000000, v68
	v_fmac_f32_e32 v66, 0xba000000, v72
	v_mul_f32_e32 v16, v67, v67
	v_mul_f32_e32 v17, v65, v65
	v_fmac_f32_e32 v16, v66, v66
	v_fmac_f32_e32 v17, v64, v64
	v_fmamk_f32 v57, v72, 0xba000000, v61
	v_fmamk_f32 v59, v72, 0xba000000, v59
	v_add_f32_e32 v16, v16, v17
	v_fmamk_f32 v56, v72, 0xba000000, v60
	v_fmac_f32_e32 v58, 0xba000000, v72
	v_mul_f32_e32 v17, v59, v59
	v_mul_f32_e32 v24, v57, v57
	v_fmac_f32_e32 v17, v58, v58
	v_fmac_f32_e32 v24, v56, v56
	v_add_f32_e32 v17, v17, v24
	v_fmamk_f32 v49, v72, 0xba000000, v53
	v_fmamk_f32 v51, v72, 0xba000000, v51
	v_add_f32_e32 v16, v16, v17
	v_fmamk_f32 v48, v72, 0xba000000, v52
	v_fmac_f32_e32 v50, 0xba000000, v72
	v_mul_f32_e32 v17, v51, v51
	v_mul_f32_e32 v24, v49, v49
	v_fmac_f32_e32 v17, v50, v50
	v_fmac_f32_e32 v24, v48, v48
	v_add_f32_e32 v17, v17, v24
	v_fmamk_f32 v41, v72, 0xba000000, v45
	v_fmamk_f32 v43, v72, 0xba000000, v43
	v_add_f32_e32 v16, v17, v16
	v_fmamk_f32 v40, v72, 0xba000000, v44
	v_fmac_f32_e32 v42, 0xba000000, v72
	v_mul_f32_e32 v17, v43, v43
	v_mul_f32_e32 v24, v41, v41
	v_fmac_f32_e32 v17, v42, v42
	v_fmac_f32_e32 v24, v40, v40
	v_add_f32_e32 v17, v17, v24
	v_fmamk_f32 v33, v72, 0xba000000, v37
	v_fmamk_f32 v35, v72, 0xba000000, v35
	v_add_f32_e32 v16, v17, v16
	v_fmamk_f32 v32, v72, 0xba000000, v36
	v_fmac_f32_e32 v34, 0xba000000, v72
	v_mul_f32_e32 v17, v35, v35
	v_mul_f32_e32 v24, v33, v33
	v_fmac_f32_e32 v17, v34, v34
	v_fmac_f32_e32 v24, v32, v32
	v_add_f32_e32 v17, v17, v24
	v_fmamk_f32 v25, v72, 0xba000000, v29
	v_fmamk_f32 v27, v72, 0xba000000, v27
	v_add_f32_e32 v16, v17, v16
	v_fmamk_f32 v24, v72, 0xba000000, v28
	v_fmac_f32_e32 v26, 0xba000000, v72
	v_mul_f32_e32 v17, v27, v27
	v_mul_f32_e32 v28, v25, v25
	v_fmac_f32_e32 v17, v26, v26
	v_fmac_f32_e32 v28, v24, v24
	v_add_f32_e32 v17, v17, v28
	v_add_f32_e32 v28, v17, v16
	v_fmamk_f32 v17, v72, 0xba000000, v21
	v_fmamk_f32 v19, v72, 0xba000000, v19
	v_fmamk_f32 v16, v72, 0xba000000, v20
	v_fmac_f32_e32 v18, 0xba000000, v72
	v_mul_f32_e32 v20, v19, v19
	v_mul_f32_e32 v21, v17, v17
	v_fmamk_f32 v151, v72, 0xba000000, v13
	v_fmamk_f32 v11, v72, 0xba000000, v11
	v_fmac_f32_e32 v20, v18, v18
	v_fmac_f32_e32 v21, v16, v16
	v_fmamk_f32 v150, v72, 0xba000000, v12
	v_fmac_f32_e32 v10, 0xba000000, v72
	v_mul_f32_e32 v12, v11, v11
	v_mul_f32_e32 v13, v151, v151
	v_add_f32_e32 v20, v20, v21
	v_fmac_f32_e32 v12, v10, v10
	v_fmac_f32_e32 v13, v150, v150
	v_add_f32_e32 v20, v20, v28
	v_add_f32_e32 v12, v12, v13
	v_add_f32_e32 v12, v12, v20
	v_mov_b32_e32 v28, 0
	v_mov_b32_e32 v29, 0
	v_add_f32_dpp v12, v12, v12 quad_perm:[1,0,3,2] row_mask:0xf bank_mask:0xf bound_ctrl:1
	v_mov_b32_e32 v72, 0
	s_nop 0
	v_add_f32_dpp v12, v12, v12 quad_perm:[2,3,0,1] row_mask:0xf bank_mask:0xf bound_ctrl:1
	s_nop 1
	v_add_f32_dpp v12, v12, v12 row_half_mirror row_mask:0xf bank_mask:0xf bound_ctrl:1
	s_nop 1
	v_add_f32_dpp v12, v12, v12 row_mirror row_mask:0xf bank_mask:0xf bound_ctrl:1
	v_mov_b32_e32 v13, v12
	s_nop 1
	v_permlane16_swap_b32_e32 v12, v13
	v_add_f32_e32 v13, v12, v13
	v_mov_b32_e32 v20, v13
	v_cndmask_b32_e64 v12, 0, 1, s[10:11]
	s_nop 0
	v_permlane32_swap_b32_e32 v13, v20
	v_cmp_ne_u32_e64 s[6:7], 1, v12
	s_cbranch_vccnz .LBB0_1333
	ds_read_b128 v[72:75], v252 offset:16384
	s_waitcnt lgkmcnt(0)
	v_pk_add_f32 v[28:29], v[74:75], 1.0 op_sel_hi:[1,0]
	v_pk_add_f32 v[164:165], v[72:73], 1.0 op_sel_hi:[1,0]
	ds_read_b128 v[72:75], v252 offset:24576
; __device__ __forceinline__ unsigned cvt_pk_bf16(float lo, float hi) { unsigned r; asm volatile("v_cvt_pk_bf16_f32 %0, %1, %2" : "=v"(r) : "v"(lo), "v"(hi)); return r; }
; __device__ __forceinline__ void phase_ln(const float* z, float* xo, const float* __restrict__ g, const float* __restrict__ b, const float* __restrict__ sc, const float* __restrict__ sh, bf16_t* __restrict__ u) {
;     ...
;             rstd[k] = 1.0f / sqrtf(wave_sum(q) * (1.0f / DM) + 1e-5f); }
; #pragma unroll
;         for (int j = 0; j < 8; ++j) { const int col = j * 256 + 4 * lane;
;             const f32x4 gg = *(const f32x4*)(g + col), bb = *(const f32x4*)(b + col);
;             f32x4 s1 = {0.f, 0.f, 0.f, 0.f}, h1 = {0.f, 0.f, 0.f, 0.f};
;             if (u) { s1 = *(const f32x4*)(sc + col) + 1.0f; h1 = *(const f32x4*)(sh + col); }
; #pragma unroll
;             for (int k = 0; k < 2; ++k) { if (k == 1 && !hasB) continue;
;                 const f32x4 o = (v[k][j] - mean[k]) * rstd[k] * gg + bb;
;                 *(f32x4*)(xo + (size_t)rr[k] * DM + col) = o;
;                 if (u) { const f32x4 m = o * s1 + h1; u32x2 w; w.x = cvt_pk_bf16(m[0], m[1]); w.y = cvt_pk_bf16(m[2], m[3]); *(u32x2*)(u + (size_t)rr[k] * DM + col) = w; } } }
.LBB0_1333:
	v_add_f32_e32 v12, v77, v156
	v_fmamk_f32 v12, v12, 0x3a000000, v220
	v_mul_f32_e32 v21, 0x4f800000, v12
	v_cmp_gt_f32_e32 vcc, s77, v12
	s_nop 1
	v_cndmask_b32_e32 v12, v12, v21, vcc
	v_sqrt_f32_e32 v21, v12
	s_nop 0
	v_add_u32_e32 v36, -1, v21
	v_fma_f32 v44, -v36, v21, v12
	v_add_u32_e32 v37, 1, v21
	v_cmp_ge_f32_e64 s[0:1], 0, v44
	s_nop 1
	v_cndmask_b32_e64 v36, v21, v36, s[0:1]
	v_fma_f32 v21, -v37, v21, v12
	v_cmp_lt_f32_e64 s[0:1], 0, v21
	s_nop 1
	v_cndmask_b32_e64 v21, v36, v37, s[0:1]
	v_mul_f32_e32 v36, 0x37800000, v21
	v_cndmask_b32_e32 v21, v21, v36, vcc
	v_cmp_class_f32_e32 vcc, v12, v219
	s_nop 1
	v_cndmask_b32_e32 v12, v21, v12, vcc
	v_div_scale_f32 v21, s[0:1], v12, v12, 1.0
	v_rcp_f32_e32 v36, v21
	s_nop 0
	v_fma_f32 v37, -v21, v36, 1.0
	v_fmac_f32_e32 v36, v37, v36
	v_div_scale_f32 v37, vcc, 1.0, v12, 1.0
	v_mul_f32_e32 v44, v37, v36
	v_fma_f32 v45, -v21, v44, v37
	v_fmac_f32_e32 v44, v45, v36
	v_fma_f32 v21, -v21, v44, v37
	v_div_fmas_f32 v21, v21, v36, v44
	v_div_fixup_f32 v12, v21, v12, 1.0
	v_pk_mul_f32 v[36:37], v[70:71], v[12:13] op_sel_hi:[1,0]
	v_pk_mul_f32 v[44:45], v[154:155], v[12:13] op_sel_hi:[1,0]
	v_pk_fma_f32 v[68:69], v[2:3], v[36:37], v[6:7]
	v_pk_fma_f32 v[70:71], v[4:5], v[44:45], v[8:9]
	v_lshl_add_u64 v[154:155], v[142:143], 0, v[0:1]
	s_and_b64 vcc, exec, s[6:7]
	flat_store_dwordx4 v[154:155], v[68:71]
	s_cbranch_vccnz .LBB0_1335
	s_waitcnt lgkmcnt(0)
	v_pk_fma_f32 v[44:45], v[68:69], v[164:165], v[72:73]
	v_pk_fma_f32 v[36:37], v[70:71], v[28:29], v[74:75]
	v_cvt_pk_bf16_f32 v44, v44, v45
	s_nop 0
	v_cvt_pk_bf16_f32 v45, v36, v37
	flat_store_dwordx2 v[140:141], v[44:45]
.LBB0_1335:
	v_add_f32_e32 v13, v13, v20
	v_fmamk_f32 v13, v13, 0x3a000000, v220
	v_mul_f32_e32 v20, 0x4f800000, v13
	v_cmp_gt_f32_e32 vcc, s77, v13
	s_nop 1
	v_cndmask_b32_e32 v13, v13, v20, vcc
	v_sqrt_f32_e32 v20, v13
	s_nop 0
	v_add_u32_e32 v21, -1, v20
	v_fma_f32 v37, -v21, v20, v13
	v_add_u32_e32 v36, 1, v20
	v_cmp_ge_f32_e64 s[0:1], 0, v37
	s_nop 1
	v_cndmask_b32_e64 v21, v20, v21, s[0:1]
	v_fma_f32 v20, -v36, v20, v13
	v_cmp_lt_f32_e64 s[0:1], 0, v20
	s_nop 1
	v_cndmask_b32_e64 v20, v21, v36, s[0:1]
	v_mul_f32_e32 v21, 0x37800000, v20
	v_cndmask_b32_e32 v20, v20, v21, vcc
	v_cmp_class_f32_e32 vcc, v13, v219
	s_nop 1
	v_cndmask_b32_e32 v13, v20, v13, vcc
	v_div_scale_f32 v20, s[0:1], v13, v13, 1.0
	v_rcp_f32_e32 v21, v20
	s_nop 0
	v_fma_f32 v36, -v20, v21, 1.0
	v_fmac_f32_e32 v21, v36, v21
	v_div_scale_f32 v36, vcc, 1.0, v13, 1.0
	v_mul_f32_e32 v37, v36, v21
	v_fma_f32 v44, -v20, v37, v36
	v_fmac_f32_e32 v37, v44, v21
	v_fma_f32 v20, -v20, v37, v36
	v_div_fmas_f32 v20, v20, v21, v37
	v_div_fixup_f32 v156, v20, v13, 1.0
	v_lshl_add_u64 v[20:21], v[88:89], 0, v[146:147]
	s_and_saveexec_b64 s[0:1], s[4:5]
	s_cbranch_execz .LBB0_1338
	v_pk_mul_f32 v[36:37], v[64:65], v[156:157] op_sel_hi:[1,0]
	v_pk_mul_f32 v[44:45], v[66:67], v[156:157] op_sel_hi:[1,0]
	v_pk_fma_f32 v[66:67], v[4:5], v[36:37], v[8:9]
	v_pk_fma_f32 v[64:65], v[2:3], v[44:45], v[6:7]
	s_and_b64 vcc, exec, s[6:7]
	flat_store_dwordx4 v[20:21], v[64:67]
	s_cbranch_vccnz .LBB0_1338
	s_waitcnt lgkmcnt(0)
	v_pk_fma_f32 v[28:29], v[66:67], v[28:29], v[74:75]
	v_pk_fma_f32 v[36:37], v[64:65], v[164:165], v[72:73]
	s_nop 0
	v_cvt_pk_bf16_f32 v36, v36, v37
	v_cvt_pk_bf16_f32 v37, v28, v29
	v_lshlrev_b64 v[28:29], 12, v[144:145]
	v_lshl_add_u64 v[28:29], v[90:91], 0, v[28:29]
	flat_store_dwordx2 v[28:29], v[36:37]
.LBB0_1338:
	s_or_b64 exec, exec, s[0:1]
	ds_read_b128 v[64:67], v252 offset:1024
	ds_read_b128 v[68:71], v252 offset:9216
	s_and_b64 vcc, exec, s[6:7]
	s_cbranch_vccnz .LBB0_1340
	s_waitcnt lgkmcnt(0)
	ds_read_b128 v[72:75], v252 offset:17408
	s_waitcnt lgkmcnt(0)
	v_pk_add_f32 v[36:37], v[74:75], 1.0 op_sel_hi:[1,0]
	v_pk_add_f32 v[28:29], v[72:73], 1.0 op_sel_hi:[1,0]
	ds_read_b128 v[72:75], v252 offset:25600
	s_branch .LBB0_1341
.LBB0_1340:
	v_mov_b32_e32 v28, 0
	v_mov_b32_e32 v29, v28
	v_mov_b32_e32 v36, v28
	v_mov_b32_e32 v37, v28
	s_waitcnt lgkmcnt(0)
	v_mov_b32_e32 v72, v28
	v_mov_b32_e32 v73, v28
	v_mov_b32_e32 v74, v28
	v_mov_b32_e32 v75, v28
.LBB0_1341:
	v_mov_b32_e32 v13, v12
	v_mov_b32_e32 v44, v12
	v_mov_b32_e32 v45, v12
	v_pk_mul_f32 v[44:45], v[168:169], v[44:45]
	v_pk_mul_f32 v[52:53], v[62:63], v[12:13]
	v_pk_fma_f32 v[62:63], v[44:45], v[66:67], v[70:71]
	v_pk_fma_f32 v[60:61], v[52:53], v[64:65], v[68:69]
	s_and_b64 vcc, exec, s[6:7]
	flat_store_dwordx4 v[154:155], v[60:63] offset:1024
	s_cbranch_vccnz .LBB0_1343
	s_waitcnt lgkmcnt(0)
	v_pk_fma_f32 v[52:53], v[60:61], v[28:29], v[72:73]
	v_pk_fma_f32 v[44:45], v[62:63], v[36:37], v[74:75]
	v_cvt_pk_bf16_f32 v52, v52, v53
	s_nop 0
	v_cvt_pk_bf16_f32 v53, v44, v45
	flat_store_dwordx2 v[140:141], v[52:53] offset:512
.LBB0_1343:
	s_and_saveexec_b64 s[0:1], s[4:5]
	s_cbranch_execz .LBB0_1346
	v_pk_mul_f32 v[44:45], v[56:57], v[156:157] op_sel_hi:[1,0]
	v_pk_mul_f32 v[52:53], v[58:59], v[156:157] op_sel_hi:[1,0]
	v_pk_fma_f32 v[58:59], v[44:45], v[66:67], v[70:71]
	v_pk_fma_f32 v[56:57], v[52:53], v[64:65], v[68:69]
	s_and_b64 vcc, exec, s[6:7]
	flat_store_dwordx4 v[20:21], v[56:59] offset:1024
	s_cbranch_vccnz .LBB0_1346
	s_waitcnt lgkmcnt(0)
	v_pk_fma_f32 v[36:37], v[58:59], v[36:37], v[74:75]
	v_pk_fma_f32 v[28:29], v[56:57], v[28:29], v[72:73]
	s_nop 0
	v_cvt_pk_bf16_f32 v28, v28, v29
	v_cvt_pk_bf16_f32 v29, v36, v37
	v_lshlrev_b64 v[36:37], 12, v[144:145]
	v_lshl_add_u64 v[36:37], v[90:91], 0, v[36:37]
	flat_store_dwordx2 v[36:37], v[28:29] offset:512
.LBB0_1346:
	s_or_b64 exec, exec, s[0:1]
	ds_read_b128 v[56:59], v252 offset:2048
	ds_read_b128 v[60:63], v252 offset:10240
	s_and_b64 vcc, exec, s[6:7]
	s_cbranch_vccnz .LBB0_1348
	ds_read_b128 v[64:67], v252 offset:18432
	s_waitcnt lgkmcnt(0)
	v_pk_add_f32 v[36:37], v[66:67], 1.0 op_sel_hi:[1,0]
	v_pk_add_f32 v[28:29], v[64:65], 1.0 op_sel_hi:[1,0]
	ds_read_b128 v[64:67], v252 offset:26624
	s_branch .LBB0_1349

; __device__ __forceinline__ unsigned cvt_pk_bf16(float lo, float hi) { unsigned r; asm volatile("v_cvt_pk_bf16_f32 %0, %1, %2" : "=v"(r) : "v"(lo), "v"(hi)); return r; }
; __device__ __forceinline__ void phase_ln(const float* z, float* xo, const float* __restrict__ g, const float* __restrict__ b, const float* __restrict__ sc, const float* __restrict__ sh, bf16_t* __restrict__ u) {
;     ...
;             for (int k = 0; k < 2; ++k) { if (k == 1 && !hasB) continue;
;                 const f32x4 o = (v[k][j] - mean[k]) * rstd[k] * gg + bb;
;                 *(f32x4*)(xo + (size_t)rr[k] * DM + col) = o;
;                 if (u) { const f32x4 m = o * s1 + h1; u32x2 w; w.x = cvt_pk_bf16(m[0], m[1]); w.y = cvt_pk_bf16(m[2], m[3]); *(u32x2*)(u + (size_t)rr[k] * DM + col) = w; } } }
.LBB0_1349:
	v_mov_b32_e32 v44, v12
	v_mov_b32_e32 v45, v12
	v_pk_mul_f32 v[44:45], v[166:167], v[44:45]
	v_pk_mul_f32 v[52:53], v[54:55], v[12:13]
	s_waitcnt lgkmcnt(0)
	v_pk_fma_f32 v[54:55], v[44:45], v[58:59], v[62:63]
	v_pk_fma_f32 v[52:53], v[52:53], v[56:57], v[60:61]
	s_and_b64 vcc, exec, s[6:7]
	flat_store_dwordx4 v[154:155], v[52:55] offset:2048
	s_cbranch_vccnz .LBB0_1351
	s_nop 0
	v_pk_fma_f32 v[52:53], v[52:53], v[28:29], v[64:65]
	v_pk_fma_f32 v[44:45], v[54:55], v[36:37], v[66:67]
	v_cvt_pk_bf16_f32 v52, v52, v53
	s_nop 0
	v_cvt_pk_bf16_f32 v53, v44, v45
	flat_store_dwordx2 v[140:141], v[52:53] offset:1024

; __device__ __forceinline__ void phase_ln(const float* z, float* xo, const float* __restrict__ g, const float* __restrict__ b, const float* __restrict__ sc, const float* __restrict__ sh, bf16_t* __restrict__ u) {
;     ...
;             const f32x4 gg = *(const f32x4*)(g + col), bb = *(const f32x4*)(b + col);
;             f32x4 s1 = {0.f, 0.f, 0.f, 0.f}, h1 = {0.f, 0.f, 0.f, 0.f};
;             if (u) { s1 = *(const f32x4*)(sc + col) + 1.0f; h1 = *(const f32x4*)(sh + col); }
.LBB0_1354:
	s_or_b64 exec, exec, s[0:1]
	ds_read_b128 v[48:51], v252 offset:3072
	ds_read_b128 v[52:55], v252 offset:11264
	s_and_b64 vcc, exec, s[6:7]
	s_cbranch_vccnz .LBB0_1356
	ds_read_b128 v[56:59], v252 offset:19456
	s_waitcnt lgkmcnt(0)
	v_pk_add_f32 v[36:37], v[58:59], 1.0 op_sel_hi:[1,0]
	v_pk_add_f32 v[28:29], v[56:57], 1.0 op_sel_hi:[1,0]
	ds_read_b128 v[56:59], v252 offset:27648
	s_branch .LBB0_1357

; __device__ __forceinline__ unsigned cvt_pk_bf16(float lo, float hi) { unsigned r; asm volatile("v_cvt_pk_bf16_f32 %0, %1, %2" : "=v"(r) : "v"(lo), "v"(hi)); return r; }
; __device__ __forceinline__ void phase_ln(const float* z, float* xo, const float* __restrict__ g, const float* __restrict__ b, const float* __restrict__ sc, const float* __restrict__ sh, bf16_t* __restrict__ u) {
;     ...
;             for (int k = 0; k < 2; ++k) { if (k == 1 && !hasB) continue;
;                 const f32x4 o = (v[k][j] - mean[k]) * rstd[k] * gg + bb;
;                 *(f32x4*)(xo + (size_t)rr[k] * DM + col) = o;
;                 if (u) { const f32x4 m = o * s1 + h1; u32x2 w; w.x = cvt_pk_bf16(m[0], m[1]); w.y = cvt_pk_bf16(m[2], m[3]); *(u32x2*)(u + (size_t)rr[k] * DM + col) = w; } } }
.LBB0_1357:
	v_mov_b32_e32 v44, v12
	v_mov_b32_e32 v45, v12
	v_pk_mul_f32 v[44:45], v[162:163], v[44:45]
	v_pk_mul_f32 v[60:61], v[46:47], v[12:13]
	s_waitcnt lgkmcnt(0)
	v_pk_fma_f32 v[46:47], v[44:45], v[50:51], v[54:55]
	v_pk_fma_f32 v[44:45], v[60:61], v[48:49], v[52:53]
	s_and_b64 vcc, exec, s[6:7]
	flat_store_dwordx4 v[154:155], v[44:47] offset:3072
	s_cbranch_vccnz .LBB0_1359
	s_nop 0
	v_pk_fma_f32 v[44:45], v[44:45], v[28:29], v[56:57]
	v_pk_fma_f32 v[46:47], v[46:47], v[36:37], v[58:59]
	v_cvt_pk_bf16_f32 v44, v44, v45
	s_nop 0
	v_cvt_pk_bf16_f32 v45, v46, v47
	flat_store_dwordx2 v[140:141], v[44:45] offset:1536

; __device__ __forceinline__ void phase_ln(const float* z, float* xo, const float* __restrict__ g, const float* __restrict__ b, const float* __restrict__ sc, const float* __restrict__ sh, bf16_t* __restrict__ u) {
;     ...
;             const f32x4 gg = *(const f32x4*)(g + col), bb = *(const f32x4*)(b + col);
;             f32x4 s1 = {0.f, 0.f, 0.f, 0.f}, h1 = {0.f, 0.f, 0.f, 0.f};
;             if (u) { s1 = *(const f32x4*)(sc + col) + 1.0f; h1 = *(const f32x4*)(sh + col); }
.LBB0_1362:
	s_or_b64 exec, exec, s[0:1]
	ds_read_b128 v[40:43], v252 offset:4096
	ds_read_b128 v[44:47], v252 offset:12288
	s_and_b64 vcc, exec, s[6:7]
	s_cbranch_vccnz .LBB0_1364
	ds_read_b128 v[48:51], v252 offset:20480
	s_waitcnt lgkmcnt(0)
	v_pk_add_f32 v[28:29], v[50:51], 1.0 op_sel_hi:[1,0]
	v_pk_add_f32 v[20:21], v[48:49], 1.0 op_sel_hi:[1,0]
	ds_read_b128 v[48:51], v252 offset:28672
	s_branch .LBB0_1365

; __device__ __forceinline__ unsigned cvt_pk_bf16(float lo, float hi) { unsigned r; asm volatile("v_cvt_pk_bf16_f32 %0, %1, %2" : "=v"(r) : "v"(lo), "v"(hi)); return r; }
; __device__ __forceinline__ void phase_ln(const float* z, float* xo, const float* __restrict__ g, const float* __restrict__ b, const float* __restrict__ sc, const float* __restrict__ sh, bf16_t* __restrict__ u) {
;     ...
;             for (int k = 0; k < 2; ++k) { if (k == 1 && !hasB) continue;
;                 const f32x4 o = (v[k][j] - mean[k]) * rstd[k] * gg + bb;
;                 *(f32x4*)(xo + (size_t)rr[k] * DM + col) = o;
;                 if (u) { const f32x4 m = o * s1 + h1; u32x2 w; w.x = cvt_pk_bf16(m[0], m[1]); w.y = cvt_pk_bf16(m[2], m[3]); *(u32x2*)(u + (size_t)rr[k] * DM + col) = w; } } }
.LBB0_1365:
	v_mov_b32_e32 v36, v12
	v_mov_b32_e32 v37, v12
	v_pk_mul_f32 v[36:37], v[160:161], v[36:37]
	v_pk_mul_f32 v[52:53], v[38:39], v[12:13]
	s_waitcnt lgkmcnt(0)
	v_pk_fma_f32 v[38:39], v[36:37], v[42:43], v[46:47]
	v_pk_fma_f32 v[36:37], v[52:53], v[40:41], v[44:45]
	v_add_co_u32_e32 v52, vcc, 0x1000, v154
	s_nop 1
	v_addc_co_u32_e32 v53, vcc, 0, v155, vcc
	s_and_b64 vcc, exec, s[6:7]
	flat_store_dwordx4 v[52:53], v[36:39]
	s_cbranch_vccnz .LBB0_1367
	s_nop 0
	v_pk_fma_f32 v[36:37], v[36:37], v[20:21], v[48:49]
	v_pk_fma_f32 v[38:39], v[38:39], v[28:29], v[50:51]
	v_cvt_pk_bf16_f32 v36, v36, v37
	s_nop 0
	v_cvt_pk_bf16_f32 v37, v38, v39
	flat_store_dwordx2 v[140:141], v[36:37] offset:2048

; __device__ __forceinline__ void phase_ln(const float* z, float* xo, const float* __restrict__ g, const float* __restrict__ b, const float* __restrict__ sc, const float* __restrict__ sh, bf16_t* __restrict__ u) {
;     ...
;             const f32x4 gg = *(const f32x4*)(g + col), bb = *(const f32x4*)(b + col);
;             f32x4 s1 = {0.f, 0.f, 0.f, 0.f}, h1 = {0.f, 0.f, 0.f, 0.f};
;             if (u) { s1 = *(const f32x4*)(sc + col) + 1.0f; h1 = *(const f32x4*)(sh + col); }
.LBB0_1370:
	s_or_b64 exec, exec, s[0:1]
	ds_read_b128 v[32:35], v252 offset:5120
	ds_read_b128 v[36:39], v252 offset:13312
	s_and_b64 vcc, exec, s[6:7]
	s_cbranch_vccnz .LBB0_1372
	ds_read_b128 v[40:43], v252 offset:21504
	s_waitcnt lgkmcnt(0)
	v_pk_add_f32 v[44:45], v[42:43], 1.0 op_sel_hi:[1,0]
	v_pk_add_f32 v[20:21], v[40:41], 1.0 op_sel_hi:[1,0]
	ds_read_b128 v[40:43], v252 offset:29696
	s_branch .LBB0_1373

; __device__ __forceinline__ unsigned cvt_pk_bf16(float lo, float hi) { unsigned r; asm volatile("v_cvt_pk_bf16_f32 %0, %1, %2" : "=v"(r) : "v"(lo), "v"(hi)); return r; }
; __device__ __forceinline__ void phase_ln(const float* z, float* xo, const float* __restrict__ g, const float* __restrict__ b, const float* __restrict__ sc, const float* __restrict__ sh, bf16_t* __restrict__ u) {
;     ...
;             for (int k = 0; k < 2; ++k) { if (k == 1 && !hasB) continue;
;                 const f32x4 o = (v[k][j] - mean[k]) * rstd[k] * gg + bb;
;                 *(f32x4*)(xo + (size_t)rr[k] * DM + col) = o;
;                 if (u) { const f32x4 m = o * s1 + h1; u32x2 w; w.x = cvt_pk_bf16(m[0], m[1]); w.y = cvt_pk_bf16(m[2], m[3]); *(u32x2*)(u + (size_t)rr[k] * DM + col) = w; } } }
.LBB0_1373:
	v_mov_b32_e32 v28, v12
	v_mov_b32_e32 v29, v12
	v_pk_mul_f32 v[28:29], v[158:159], v[28:29]
	v_pk_mul_f32 v[46:47], v[30:31], v[12:13]
	s_waitcnt lgkmcnt(0)
	v_pk_fma_f32 v[30:31], v[28:29], v[34:35], v[38:39]
	v_pk_fma_f32 v[28:29], v[46:47], v[32:33], v[36:37]
	v_add_co_u32_e32 v46, vcc, 0x1000, v154
	s_nop 1
	v_addc_co_u32_e32 v47, vcc, 0, v155, vcc
	s_and_b64 vcc, exec, s[6:7]
	flat_store_dwordx4 v[46:47], v[28:31] offset:1024
	s_cbranch_vccnz .LBB0_1375
	s_nop 0
	v_pk_fma_f32 v[28:29], v[28:29], v[20:21], v[40:41]
	v_pk_fma_f32 v[30:31], v[30:31], v[44:45], v[42:43]
	v_cvt_pk_bf16_f32 v28, v28, v29
	s_nop 0
	v_cvt_pk_bf16_f32 v29, v30, v31
	flat_store_dwordx2 v[140:141], v[28:29] offset:2560

; __device__ __forceinline__ void phase_ln(const float* z, float* xo, const float* __restrict__ g, const float* __restrict__ b, const float* __restrict__ sc, const float* __restrict__ sh, bf16_t* __restrict__ u) {
;     ...
;             const f32x4 gg = *(const f32x4*)(g + col), bb = *(const f32x4*)(b + col);
;             f32x4 s1 = {0.f, 0.f, 0.f, 0.f}, h1 = {0.f, 0.f, 0.f, 0.f};
;             if (u) { s1 = *(const f32x4*)(sc + col) + 1.0f; h1 = *(const f32x4*)(sh + col); }
.LBB0_1378:
	s_or_b64 exec, exec, s[0:1]
	ds_read_b128 v[24:27], v252 offset:6144
	ds_read_b128 v[28:31], v252 offset:14336
	s_and_b64 vcc, exec, s[6:7]
	s_cbranch_vccnz .LBB0_1380
	ds_read_b128 v[32:35], v252 offset:22528
	s_waitcnt lgkmcnt(0)
	v_pk_add_f32 v[38:39], v[34:35], 1.0 op_sel_hi:[1,0]
	v_pk_add_f32 v[36:37], v[32:33], 1.0 op_sel_hi:[1,0]
	ds_read_b128 v[32:35], v252 offset:30720
	s_branch .LBB0_1381

; __device__ __forceinline__ unsigned cvt_pk_bf16(float lo, float hi) { unsigned r; asm volatile("v_cvt_pk_bf16_f32 %0, %1, %2" : "=v"(r) : "v"(lo), "v"(hi)); return r; }
; __device__ __forceinline__ void phase_ln(const float* z, float* xo, const float* __restrict__ g, const float* __restrict__ b, const float* __restrict__ sc, const float* __restrict__ sh, bf16_t* __restrict__ u) {
;     ...
;             for (int k = 0; k < 2; ++k) { if (k == 1 && !hasB) continue;
;                 const f32x4 o = (v[k][j] - mean[k]) * rstd[k] * gg + bb;
;                 *(f32x4*)(xo + (size_t)rr[k] * DM + col) = o;
;                 if (u) { const f32x4 m = o * s1 + h1; u32x2 w; w.x = cvt_pk_bf16(m[0], m[1]); w.y = cvt_pk_bf16(m[2], m[3]); *(u32x2*)(u + (size_t)rr[k] * DM + col) = w; } } }
.LBB0_1381:
	v_mov_b32_e32 v20, v12
	v_mov_b32_e32 v21, v12
	v_pk_mul_f32 v[20:21], v[152:153], v[20:21]
	v_pk_mul_f32 v[40:41], v[22:23], v[12:13]
	s_waitcnt lgkmcnt(0)
	v_pk_fma_f32 v[22:23], v[20:21], v[26:27], v[30:31]
	v_pk_fma_f32 v[20:21], v[40:41], v[24:25], v[28:29]
	v_add_co_u32_e32 v40, vcc, 0x1000, v154
	s_nop 1
	v_addc_co_u32_e32 v41, vcc, 0, v155, vcc
	s_and_b64 vcc, exec, s[6:7]
	flat_store_dwordx4 v[40:41], v[20:23] offset:2048
	s_cbranch_vccnz .LBB0_1383
	s_nop 0
	v_pk_fma_f32 v[20:21], v[20:21], v[36:37], v[32:33]
	v_pk_fma_f32 v[22:23], v[22:23], v[38:39], v[34:35]
	v_cvt_pk_bf16_f32 v20, v20, v21
	s_nop 0
	v_cvt_pk_bf16_f32 v21, v22, v23
	flat_store_dwordx2 v[140:141], v[20:21] offset:3072

; __device__ __forceinline__ void phase_ln(const float* z, float* xo, const float* __restrict__ g, const float* __restrict__ b, const float* __restrict__ sc, const float* __restrict__ sh, bf16_t* __restrict__ u) {
;     ...
;             const f32x4 gg = *(const f32x4*)(g + col), bb = *(const f32x4*)(b + col);
;             f32x4 s1 = {0.f, 0.f, 0.f, 0.f}, h1 = {0.f, 0.f, 0.f, 0.f};
;             if (u) { s1 = *(const f32x4*)(sc + col) + 1.0f; h1 = *(const f32x4*)(sh + col); }
.LBB0_1386:
	s_or_b64 exec, exec, s[0:1]
	ds_read_b128 v[16:19], v252 offset:7168
	ds_read_b128 v[20:23], v252 offset:15360
	s_and_b64 vcc, exec, s[6:7]
	s_cbranch_vccnz .LBB0_1388
	ds_read_b128 v[24:27], v252 offset:23552
	s_waitcnt lgkmcnt(0)
	v_pk_add_f32 v[30:31], v[26:27], 1.0 op_sel_hi:[1,0]
	v_pk_add_f32 v[28:29], v[24:25], 1.0 op_sel_hi:[1,0]
	ds_read_b128 v[24:27], v252 offset:31744
	s_branch .LBB0_1389

; __device__ __forceinline__ unsigned cvt_pk_bf16(float lo, float hi) { unsigned r; asm volatile("v_cvt_pk_bf16_f32 %0, %1, %2" : "=v"(r) : "v"(lo), "v"(hi)); return r; }
; __device__ __forceinline__ void phase_ln(const float* z, float* xo, const float* __restrict__ g, const float* __restrict__ b, const float* __restrict__ sc, const float* __restrict__ sh, bf16_t* __restrict__ u) {
;     ...
;             for (int k = 0; k < 2; ++k) { if (k == 1 && !hasB) continue;
;                 const f32x4 o = (v[k][j] - mean[k]) * rstd[k] * gg + bb;
;                 *(f32x4*)(xo + (size_t)rr[k] * DM + col) = o;
;                 if (u) { const f32x4 m = o * s1 + h1; u32x2 w; w.x = cvt_pk_bf16(m[0], m[1]); w.y = cvt_pk_bf16(m[2], m[3]); *(u32x2*)(u + (size_t)rr[k] * DM + col) = w; } } }
.LBB0_1389:
	v_mov_b32_e32 v32, v12
	v_mov_b32_e32 v33, v12
	v_pk_mul_f32 v[32:33], v[148:149], v[32:33]
	v_pk_mul_f32 v[12:13], v[14:15], v[12:13]
	s_waitcnt lgkmcnt(0)
	v_pk_fma_f32 v[14:15], v[32:33], v[18:19], v[22:23]
	v_add_co_u32_e32 v32, vcc, 0x1000, v154
	v_pk_fma_f32 v[12:13], v[12:13], v[16:17], v[20:21]
	s_nop 0
	v_addc_co_u32_e32 v33, vcc, 0, v155, vcc
	s_and_b64 vcc, exec, s[6:7]
	flat_store_dwordx4 v[32:33], v[12:15] offset:3072
	s_cbranch_vccnz .LBB0_1391
	s_nop 0
	v_pk_fma_f32 v[12:13], v[12:13], v[28:29], v[24:25]
	v_pk_fma_f32 v[14:15], v[14:15], v[30:31], v[26:27]
	v_cvt_pk_bf16_f32 v12, v12, v13
	s_nop 0
	v_cvt_pk_bf16_f32 v13, v14, v15
	flat_store_dwordx2 v[140:141], v[12:13] offset:3584
